# E39: the six K-loop heads aligned to 64-byte boundaries (.p2align 6), otherwise E30
# baseline (speedup 1.0000x reference)
.Lcm1_skip:
	.p2align 6

.LBB0_297:
	s_ashr_i32 s85, s84, 31
	s_lshl_b64 s[20:21], s[84:85], 21
	v_readlane_b32 s14, v250, 2
	v_readlane_b32 s15, v250, 3
	s_add_u32 s92, s14, s20
	s_addc_u32 s93, s15, s21
	s_and_b64 s[20:21], s[2:3], exec
	s_cselect_b32 s5, s93, s97
	s_cselect_b32 s14, s92, s96
	s_ashr_i32 s91, s90, 31
	s_lshl_b64 s[20:21], s[90:91], 21
	v_readlane_b32 s16, v251, 50
	v_readlane_b32 s17, v251, 51
	s_add_u32 s94, s16, s20
	s_addc_u32 s95, s17, s21
	s_and_b64 s[20:21], s[2:3], exec
	s_cselect_b32 s20, s95, s79
	s_cselect_b32 s21, s94, s78
	s_add_u32 s22, s78, 0x100
	s_addc_u32 s80, s79, 0
	s_add_u32 s78, s96, 0x100080
	v_mov_b32_e32 v0, 0
	s_addc_u32 s79, s97, 0
	s_mov_b32 s81, -2
	v_mov_b32_e32 v1, v0
	v_mov_b32_e32 v2, v0
	v_mov_b32_e32 v3, v0
	v_mov_b32_e32 v4, v0
	v_mov_b32_e32 v5, v0
	v_mov_b32_e32 v6, v0
	v_mov_b32_e32 v7, v0
	v_mov_b32_e32 v8, v0
	v_mov_b32_e32 v9, v0
	v_mov_b32_e32 v10, v0
	v_mov_b32_e32 v11, v0
	v_mov_b32_e32 v16, v0
	v_mov_b32_e32 v17, v0
	v_mov_b32_e32 v18, v0
	v_mov_b32_e32 v19, v0
	v_mov_b32_e32 v24, v0
	v_mov_b32_e32 v25, v0
	v_mov_b32_e32 v26, v0
	v_mov_b32_e32 v27, v0
	v_mov_b32_e32 v32, v0
	v_mov_b32_e32 v33, v0
	v_mov_b32_e32 v34, v0
	v_mov_b32_e32 v35, v0
	v_mov_b32_e32 v40, v0
	v_mov_b32_e32 v41, v0
	v_mov_b32_e32 v42, v0
	v_mov_b32_e32 v43, v0
	v_mov_b32_e32 v48, v0
	v_mov_b32_e32 v49, v0
	v_mov_b32_e32 v50, v0
	v_mov_b32_e32 v51, v0
	v_mov_b32_e32 v12, v0
	v_mov_b32_e32 v13, v0
	v_mov_b32_e32 v14, v0
	v_mov_b32_e32 v15, v0
	v_mov_b32_e32 v20, v0
	v_mov_b32_e32 v21, v0
	v_mov_b32_e32 v22, v0
	v_mov_b32_e32 v23, v0
	v_mov_b32_e32 v28, v0
	v_mov_b32_e32 v29, v0
	v_mov_b32_e32 v30, v0
	v_mov_b32_e32 v31, v0
	v_mov_b32_e32 v36, v0
	v_mov_b32_e32 v37, v0
	v_mov_b32_e32 v38, v0
	v_mov_b32_e32 v39, v0
	v_mov_b32_e32 v44, v0
	v_mov_b32_e32 v45, v0
	v_mov_b32_e32 v46, v0
	v_mov_b32_e32 v47, v0
	v_mov_b32_e32 v52, v0
	v_mov_b32_e32 v53, v0
	v_mov_b32_e32 v54, v0
	v_mov_b32_e32 v55, v0
	v_mov_b32_e32 v56, v0
	v_mov_b32_e32 v57, v0
	v_mov_b32_e32 v58, v0
	v_mov_b32_e32 v59, v0
	v_mov_b32_e32 v60, v0
	v_mov_b32_e32 v61, v0
	v_mov_b32_e32 v62, v0
	v_mov_b32_e32 v63, v0
	v_mov_b32_e32 v64, v0
	v_mov_b32_e32 v65, v0
	v_mov_b32_e32 v66, v0
	v_mov_b32_e32 v67, v0
	v_mov_b32_e32 v68, v0
	v_mov_b32_e32 v69, v0
	v_mov_b32_e32 v70, v0
	v_mov_b32_e32 v71, v0
	v_mov_b32_e32 v72, v0
	v_mov_b32_e32 v73, v0
	v_mov_b32_e32 v74, v0
	v_mov_b32_e32 v75, v0
	v_mov_b32_e32 v80, v0
	v_mov_b32_e32 v81, v0
	v_mov_b32_e32 v82, v0
	v_mov_b32_e32 v83, v0
	v_mov_b32_e32 v88, v0
	v_mov_b32_e32 v89, v0
	v_mov_b32_e32 v90, v0
	v_mov_b32_e32 v91, v0
	v_mov_b32_e32 v96, v0
	v_mov_b32_e32 v97, v0
	v_mov_b32_e32 v98, v0
	v_mov_b32_e32 v99, v0
	v_mov_b32_e32 v104, v0
	v_mov_b32_e32 v105, v0
	v_mov_b32_e32 v106, v0
	v_mov_b32_e32 v107, v0
	v_mov_b32_e32 v116, v0
	v_mov_b32_e32 v117, v0
	v_mov_b32_e32 v118, v0
	v_mov_b32_e32 v119, v0
	v_mov_b32_e32 v76, v0
	v_mov_b32_e32 v77, v0
	v_mov_b32_e32 v78, v0
	v_mov_b32_e32 v79, v0
	v_mov_b32_e32 v84, v0
	v_mov_b32_e32 v85, v0
	v_mov_b32_e32 v86, v0
	v_mov_b32_e32 v87, v0
	v_mov_b32_e32 v92, v0
	v_mov_b32_e32 v93, v0
	v_mov_b32_e32 v94, v0
	v_mov_b32_e32 v95, v0
	v_mov_b32_e32 v100, v0
	v_mov_b32_e32 v101, v0
	v_mov_b32_e32 v102, v0
	v_mov_b32_e32 v103, v0
	v_mov_b32_e32 v108, v0
	v_mov_b32_e32 v109, v0
	v_mov_b32_e32 v110, v0
	v_mov_b32_e32 v111, v0
	v_mov_b32_e32 v112, v0
	v_mov_b32_e32 v113, v0
	v_mov_b32_e32 v114, v0
	v_mov_b32_e32 v115, v0
	v_mov_b32_e32 v120, v0
	v_mov_b32_e32 v121, v0
	v_mov_b32_e32 v122, v0
	v_mov_b32_e32 v123, v0
	v_mov_b32_e32 v124, v0
	v_mov_b32_e32 v125, v0
	v_mov_b32_e32 v126, v0
	v_mov_b32_e32 v127, v0
	.p2align 6

.LBB0_626:
	s_ashr_i32 s49, s48, 31
	s_lshl_b64 s[54:55], s[48:49], 21
	s_add_u32 s54, s0, s54
	s_addc_u32 s55, s1, s55
	s_and_b64 s[56:57], s[2:3], exec
	s_cselect_b32 s5, s55, s63
	s_cselect_b32 s49, s54, s62
	s_ashr_i32 s47, s46, 31
	s_lshl_b64 s[56:57], s[46:47], 21
	v_readlane_b32 s12, v251, 52
	v_readlane_b32 s13, v251, 53
	s_add_u32 s56, s12, s56
	s_addc_u32 s57, s13, s57
	s_and_b64 s[74:75], s[2:3], exec
	s_cselect_b32 s47, s57, s61
	s_cselect_b32 s59, s56, s60
	s_add_u32 s74, s60, 0x100
	s_addc_u32 s75, s61, 0
	s_add_u32 s60, s62, 0x100080
	v_mov_b32_e32 v0, 0
	s_addc_u32 s61, s63, 0
	s_mov_b32 s62, -2
	v_mov_b32_e32 v1, v0
	v_mov_b32_e32 v2, v0
	v_mov_b32_e32 v3, v0
	v_mov_b32_e32 v4, v0
	v_mov_b32_e32 v5, v0
	v_mov_b32_e32 v6, v0
	v_mov_b32_e32 v7, v0
	v_mov_b32_e32 v8, v0
	v_mov_b32_e32 v9, v0
	v_mov_b32_e32 v10, v0
	v_mov_b32_e32 v11, v0
	v_mov_b32_e32 v12, v0
	v_mov_b32_e32 v13, v0
	v_mov_b32_e32 v14, v0
	v_mov_b32_e32 v15, v0
	v_mov_b32_e32 v16, v0
	v_mov_b32_e32 v17, v0
	v_mov_b32_e32 v18, v0
	v_mov_b32_e32 v19, v0
	v_mov_b32_e32 v20, v0
	v_mov_b32_e32 v21, v0
	v_mov_b32_e32 v22, v0
	v_mov_b32_e32 v23, v0
	v_mov_b32_e32 v24, v0
	v_mov_b32_e32 v25, v0
	v_mov_b32_e32 v26, v0
	v_mov_b32_e32 v27, v0
	v_mov_b32_e32 v28, v0
	v_mov_b32_e32 v29, v0
	v_mov_b32_e32 v30, v0
	v_mov_b32_e32 v31, v0
	v_mov_b32_e32 v32, v0
	v_mov_b32_e32 v33, v0
	v_mov_b32_e32 v34, v0
	v_mov_b32_e32 v35, v0
	v_mov_b32_e32 v36, v0
	v_mov_b32_e32 v37, v0
	v_mov_b32_e32 v38, v0
	v_mov_b32_e32 v39, v0
	v_mov_b32_e32 v40, v0
	v_mov_b32_e32 v41, v0
	v_mov_b32_e32 v42, v0
	v_mov_b32_e32 v43, v0
	v_mov_b32_e32 v44, v0
	v_mov_b32_e32 v45, v0
	v_mov_b32_e32 v46, v0
	v_mov_b32_e32 v47, v0
	v_mov_b32_e32 v48, v0
	v_mov_b32_e32 v49, v0
	v_mov_b32_e32 v50, v0
	v_mov_b32_e32 v51, v0
	v_mov_b32_e32 v52, v0
	v_mov_b32_e32 v53, v0
	v_mov_b32_e32 v54, v0
	v_mov_b32_e32 v55, v0
	v_mov_b32_e32 v56, v0
	v_mov_b32_e32 v57, v0
	v_mov_b32_e32 v58, v0
	v_mov_b32_e32 v59, v0
	v_mov_b32_e32 v60, v0
	v_mov_b32_e32 v61, v0
	v_mov_b32_e32 v62, v0
	v_mov_b32_e32 v63, v0
	v_mov_b32_e32 v64, v0
	v_mov_b32_e32 v65, v0
	v_mov_b32_e32 v66, v0
	v_mov_b32_e32 v67, v0
	v_mov_b32_e32 v68, v0
	v_mov_b32_e32 v69, v0
	v_mov_b32_e32 v70, v0
	v_mov_b32_e32 v71, v0
	v_mov_b32_e32 v72, v0
	v_mov_b32_e32 v73, v0
	v_mov_b32_e32 v74, v0
	v_mov_b32_e32 v75, v0
	v_mov_b32_e32 v76, v0
	v_mov_b32_e32 v77, v0
	v_mov_b32_e32 v78, v0
	v_mov_b32_e32 v79, v0
	v_mov_b32_e32 v80, v0
	v_mov_b32_e32 v81, v0
	v_mov_b32_e32 v82, v0
	v_mov_b32_e32 v83, v0
	v_mov_b32_e32 v84, v0
	v_mov_b32_e32 v85, v0
	v_mov_b32_e32 v86, v0
	v_mov_b32_e32 v87, v0
	v_mov_b32_e32 v88, v0
	v_mov_b32_e32 v89, v0
	v_mov_b32_e32 v90, v0
	v_mov_b32_e32 v91, v0
	v_mov_b32_e32 v92, v0
	v_mov_b32_e32 v93, v0
	v_mov_b32_e32 v94, v0
	v_mov_b32_e32 v95, v0
	v_mov_b32_e32 v96, v0
	v_mov_b32_e32 v97, v0
	v_mov_b32_e32 v98, v0
	v_mov_b32_e32 v99, v0
	v_mov_b32_e32 v100, v0
	v_mov_b32_e32 v101, v0
	v_mov_b32_e32 v102, v0
	v_mov_b32_e32 v103, v0
	v_mov_b32_e32 v104, v0
	v_mov_b32_e32 v105, v0
	v_mov_b32_e32 v106, v0
	v_mov_b32_e32 v107, v0
	v_mov_b32_e32 v108, v0
	v_mov_b32_e32 v109, v0
	v_mov_b32_e32 v110, v0
	v_mov_b32_e32 v111, v0
	v_mov_b32_e32 v112, v0
	v_mov_b32_e32 v113, v0
	v_mov_b32_e32 v114, v0
	v_mov_b32_e32 v115, v0
	v_mov_b32_e32 v116, v0
	v_mov_b32_e32 v117, v0
	v_mov_b32_e32 v118, v0
	v_mov_b32_e32 v119, v0
	v_mov_b32_e32 v120, v0
	v_mov_b32_e32 v121, v0
	v_mov_b32_e32 v122, v0
	v_mov_b32_e32 v123, v0
	v_mov_b32_e32 v124, v0
	v_mov_b32_e32 v125, v0
	v_mov_b32_e32 v126, v0
	v_mov_b32_e32 v127, v0
	.p2align 6

.LBB0_1033:
	s_add_u32 s62, s44, 0x100
	s_addc_u32 s63, s45, 0
	s_add_u32 s44, s46, 0x2b0080
	v_mov_b32_e32 v0, 0
	s_addc_u32 s45, s47, 0
	s_mov_b32 s46, -2
	v_mov_b32_e32 v1, v0
	v_mov_b32_e32 v2, v0
	v_mov_b32_e32 v3, v0
	v_mov_b32_e32 v4, v0
	v_mov_b32_e32 v5, v0
	v_mov_b32_e32 v6, v0
	v_mov_b32_e32 v7, v0
	v_mov_b32_e32 v8, v0
	v_mov_b32_e32 v9, v0
	v_mov_b32_e32 v10, v0
	v_mov_b32_e32 v11, v0
	v_mov_b32_e32 v12, v0
	v_mov_b32_e32 v13, v0
	v_mov_b32_e32 v14, v0
	v_mov_b32_e32 v15, v0
	v_mov_b32_e32 v16, v0
	v_mov_b32_e32 v17, v0
	v_mov_b32_e32 v18, v0
	v_mov_b32_e32 v19, v0
	v_mov_b32_e32 v20, v0
	v_mov_b32_e32 v21, v0
	v_mov_b32_e32 v22, v0
	v_mov_b32_e32 v23, v0
	v_mov_b32_e32 v24, v0
	v_mov_b32_e32 v25, v0
	v_mov_b32_e32 v26, v0
	v_mov_b32_e32 v27, v0
	v_mov_b32_e32 v28, v0
	v_mov_b32_e32 v29, v0
	v_mov_b32_e32 v30, v0
	v_mov_b32_e32 v31, v0
	v_mov_b32_e32 v32, v0
	v_mov_b32_e32 v33, v0
	v_mov_b32_e32 v34, v0
	v_mov_b32_e32 v35, v0
	v_mov_b32_e32 v36, v0
	v_mov_b32_e32 v37, v0
	v_mov_b32_e32 v38, v0
	v_mov_b32_e32 v39, v0
	v_mov_b32_e32 v40, v0
	v_mov_b32_e32 v41, v0
	v_mov_b32_e32 v42, v0
	v_mov_b32_e32 v43, v0
	v_mov_b32_e32 v44, v0
	v_mov_b32_e32 v45, v0
	v_mov_b32_e32 v46, v0
	v_mov_b32_e32 v47, v0
	v_mov_b32_e32 v48, v0
	v_mov_b32_e32 v49, v0
	v_mov_b32_e32 v50, v0
	v_mov_b32_e32 v51, v0
	v_mov_b32_e32 v52, v0
	v_mov_b32_e32 v53, v0
	v_mov_b32_e32 v54, v0
	v_mov_b32_e32 v55, v0
	v_mov_b32_e32 v56, v0
	v_mov_b32_e32 v57, v0
	v_mov_b32_e32 v58, v0
	v_mov_b32_e32 v59, v0
	v_mov_b32_e32 v60, v0
	v_mov_b32_e32 v61, v0
	v_mov_b32_e32 v62, v0
	v_mov_b32_e32 v63, v0
	v_mov_b32_e32 v64, v0
	v_mov_b32_e32 v65, v0
	v_mov_b32_e32 v66, v0
	v_mov_b32_e32 v67, v0
	v_mov_b32_e32 v68, v0
	v_mov_b32_e32 v69, v0
	v_mov_b32_e32 v70, v0
	v_mov_b32_e32 v71, v0
	v_mov_b32_e32 v72, v0
	v_mov_b32_e32 v73, v0
	v_mov_b32_e32 v74, v0
	v_mov_b32_e32 v75, v0
	v_mov_b32_e32 v76, v0
	v_mov_b32_e32 v77, v0
	v_mov_b32_e32 v78, v0
	v_mov_b32_e32 v79, v0
	v_mov_b32_e32 v80, v0
	v_mov_b32_e32 v81, v0
	v_mov_b32_e32 v82, v0
	v_mov_b32_e32 v83, v0
	v_mov_b32_e32 v84, v0
	v_mov_b32_e32 v85, v0
	v_mov_b32_e32 v86, v0
	v_mov_b32_e32 v87, v0
	v_mov_b32_e32 v88, v0
	v_mov_b32_e32 v89, v0
	v_mov_b32_e32 v90, v0
	v_mov_b32_e32 v91, v0
	v_mov_b32_e32 v92, v0
	v_mov_b32_e32 v93, v0
	v_mov_b32_e32 v94, v0
	v_mov_b32_e32 v95, v0
	v_mov_b32_e32 v96, v0
	v_mov_b32_e32 v97, v0
	v_mov_b32_e32 v98, v0
	v_mov_b32_e32 v99, v0
	v_mov_b32_e32 v100, v0
	v_mov_b32_e32 v101, v0
	v_mov_b32_e32 v102, v0
	v_mov_b32_e32 v103, v0
	v_mov_b32_e32 v104, v0
	v_mov_b32_e32 v105, v0
	v_mov_b32_e32 v106, v0
	v_mov_b32_e32 v107, v0
	v_mov_b32_e32 v108, v0
	v_mov_b32_e32 v109, v0
	v_mov_b32_e32 v110, v0
	v_mov_b32_e32 v111, v0
	v_mov_b32_e32 v112, v0
	v_mov_b32_e32 v113, v0
	v_mov_b32_e32 v114, v0
	v_mov_b32_e32 v115, v0
	v_mov_b32_e32 v116, v0
	v_mov_b32_e32 v117, v0
	v_mov_b32_e32 v118, v0
	v_mov_b32_e32 v119, v0
	v_mov_b32_e32 v120, v0
	v_mov_b32_e32 v121, v0
	v_mov_b32_e32 v122, v0
	v_mov_b32_e32 v123, v0
	v_mov_b32_e32 v124, v0
	v_mov_b32_e32 v125, v0
	v_mov_b32_e32 v126, v0
	v_mov_b32_e32 v127, v0
	.p2align 6

.LBB0_1179:
	s_ashr_i32 s39, s38, 31
	s_lshl_b64 s[40:41], s[38:39], 20
	s_add_u32 s40, s24, s40
	s_addc_u32 s41, s25, s41
	s_and_b64 s[42:43], s[0:1], exec
	s_cselect_b32 s39, s41, s49
	s_cselect_b32 s66, s40, s48
	s_ashr_i32 s37, s36, 31
	s_lshl_b64 s[42:43], s[36:37], 20
	s_add_u32 s42, s74, s42
	s_addc_u32 s43, s75, s43
	s_and_b64 s[68:69], s[0:1], exec
	s_cselect_b32 s37, s43, s47
	s_cselect_b32 s67, s42, s46
	s_add_u32 s68, s46, 0x100
	s_addc_u32 s69, s47, 0
	s_add_u32 s46, s48, 0x80080
	v_mov_b32_e32 v0, 0
	s_addc_u32 s47, s49, 0
	s_mov_b32 s48, -2
	v_mov_b32_e32 v1, v0
	v_mov_b32_e32 v2, v0
	v_mov_b32_e32 v3, v0
	v_mov_b32_e32 v4, v0
	v_mov_b32_e32 v5, v0
	v_mov_b32_e32 v6, v0
	v_mov_b32_e32 v7, v0
	v_mov_b32_e32 v8, v0
	v_mov_b32_e32 v9, v0
	v_mov_b32_e32 v10, v0
	v_mov_b32_e32 v11, v0
	v_mov_b32_e32 v12, v0
	v_mov_b32_e32 v13, v0
	v_mov_b32_e32 v14, v0
	v_mov_b32_e32 v15, v0
	v_mov_b32_e32 v16, v0
	v_mov_b32_e32 v17, v0
	v_mov_b32_e32 v18, v0
	v_mov_b32_e32 v19, v0
	v_mov_b32_e32 v20, v0
	v_mov_b32_e32 v21, v0
	v_mov_b32_e32 v22, v0
	v_mov_b32_e32 v23, v0
	v_mov_b32_e32 v24, v0
	v_mov_b32_e32 v25, v0
	v_mov_b32_e32 v26, v0
	v_mov_b32_e32 v27, v0
	v_mov_b32_e32 v28, v0
	v_mov_b32_e32 v29, v0
	v_mov_b32_e32 v30, v0
	v_mov_b32_e32 v31, v0
	v_mov_b32_e32 v64, v0
	v_mov_b32_e32 v65, v0
	v_mov_b32_e32 v66, v0
	v_mov_b32_e32 v67, v0
	v_mov_b32_e32 v68, v0
	v_mov_b32_e32 v69, v0
	v_mov_b32_e32 v70, v0
	v_mov_b32_e32 v71, v0
	v_mov_b32_e32 v72, v0
	v_mov_b32_e32 v73, v0
	v_mov_b32_e32 v74, v0
	v_mov_b32_e32 v75, v0
	v_mov_b32_e32 v76, v0
	v_mov_b32_e32 v77, v0
	v_mov_b32_e32 v78, v0
	v_mov_b32_e32 v79, v0
	v_mov_b32_e32 v80, v0
	v_mov_b32_e32 v81, v0
	v_mov_b32_e32 v82, v0
	v_mov_b32_e32 v83, v0
	v_mov_b32_e32 v84, v0
	v_mov_b32_e32 v85, v0
	v_mov_b32_e32 v86, v0
	v_mov_b32_e32 v87, v0
	v_mov_b32_e32 v88, v0
	v_mov_b32_e32 v89, v0
	v_mov_b32_e32 v90, v0
	v_mov_b32_e32 v91, v0
	v_mov_b32_e32 v92, v0
	v_mov_b32_e32 v93, v0
	v_mov_b32_e32 v94, v0
	v_mov_b32_e32 v95, v0
	v_mov_b32_e32 v32, v0
	v_mov_b32_e32 v33, v0
	v_mov_b32_e32 v34, v0
	v_mov_b32_e32 v35, v0
	v_mov_b32_e32 v36, v0
	v_mov_b32_e32 v37, v0
	v_mov_b32_e32 v38, v0
	v_mov_b32_e32 v39, v0
	v_mov_b32_e32 v40, v0
	v_mov_b32_e32 v41, v0
	v_mov_b32_e32 v42, v0
	v_mov_b32_e32 v43, v0
	v_mov_b32_e32 v44, v0
	v_mov_b32_e32 v45, v0
	v_mov_b32_e32 v46, v0
	v_mov_b32_e32 v47, v0
	v_mov_b32_e32 v48, v0
	v_mov_b32_e32 v49, v0
	v_mov_b32_e32 v50, v0
	v_mov_b32_e32 v51, v0
	v_mov_b32_e32 v52, v0
	v_mov_b32_e32 v53, v0
	v_mov_b32_e32 v54, v0
	v_mov_b32_e32 v55, v0
	v_mov_b32_e32 v56, v0
	v_mov_b32_e32 v57, v0
	v_mov_b32_e32 v58, v0
	v_mov_b32_e32 v59, v0
	v_mov_b32_e32 v60, v0
	v_mov_b32_e32 v61, v0
	v_mov_b32_e32 v62, v0
	v_mov_b32_e32 v63, v0
	v_mov_b32_e32 v96, v0
	v_mov_b32_e32 v97, v0
	v_mov_b32_e32 v98, v0
	v_mov_b32_e32 v99, v0
	v_mov_b32_e32 v100, v0
	v_mov_b32_e32 v101, v0
	v_mov_b32_e32 v102, v0
	v_mov_b32_e32 v103, v0
	v_mov_b32_e32 v104, v0
	v_mov_b32_e32 v105, v0
	v_mov_b32_e32 v106, v0
	v_mov_b32_e32 v107, v0
	v_mov_b32_e32 v108, v0
	v_mov_b32_e32 v109, v0
	v_mov_b32_e32 v110, v0
	v_mov_b32_e32 v111, v0
	v_mov_b32_e32 v120, v0
	v_mov_b32_e32 v121, v0
	v_mov_b32_e32 v122, v0
	v_mov_b32_e32 v123, v0
	v_mov_b32_e32 v124, v0
	v_mov_b32_e32 v125, v0
	v_mov_b32_e32 v126, v0
	v_mov_b32_e32 v127, v0
	v_mov_b32_e32 v134, v0
	v_mov_b32_e32 v135, v0
	v_mov_b32_e32 v136, v0
	v_mov_b32_e32 v137, v0
	v_mov_b32_e32 v138, v0
	v_mov_b32_e32 v139, v0
	v_mov_b32_e32 v140, v0
	v_mov_b32_e32 v141, v0
	.p2align 6
